# GEMM tile prologue no longer drains the previous tile's epilogue stores (vmcnt(0) removed; vmcnt is in-order so later counted waits stay valid)
# speedup vs baseline: 1.0001x; 1.0001x over previous
.Lgm_ph2_noprio:
	s_barrier
	s_load_dwordx2 s[66:67], s[0:1], 0x90
	s_load_dwordx2 s[68:69], s[0:1], 0xc0
	v_and_b32_e32 v201, 0x3ff, v0
	v_readfirstlane_b32 s80, v0
	v_and_b32_e32 v200, 31, v201
	v_bfe_u32 v214, v201, 1, 3
	v_bfe_u32 v213, v201, 5, 1
	v_xor_b32_e32 v214, v214, v213
	v_lshlrev_b32_e32 v214, 4, v214
	s_and_b32 s80, s80, 0x3ff
	s_lshr_b32 s83, s80, 6
	s_lshl_b32 s80, s80, 4
	s_lshr_b32 s84, s83, 1
	s_and_b32 s83, s83, 1
	s_mul_i32 s84, s84, 0x3000
	s_lshl_b32 s83, s83, 13
	s_add_u32 s83, s83, 0xc000
	v_lshlrev_b32_e32 v200, 7, v200
	v_or_b32_e32 v200, v200, v214
	v_add_u32_e32 v215, s84, v200
	v_add_u32_e32 v211, s83, v200
	v_xor_b32_e32 v214, 0x20, v215
	v_xor_b32_e32 v210, 0x20, v211
	v_xor_b32_e32 v213, 0x40, v215
	v_xor_b32_e32 v209, 0x40, v211
	v_xor_b32_e32 v212, 0x60, v215
	v_xor_b32_e32 v208, 0x60, v211
	v_bfe_u32 v200, v201, 4, 3
	v_and_b32_e32 v206, 7, v201
	v_xor_b32_e32 v200, v200, v206
	v_lshlrev_b32_e32 v200, 4, v200
	v_lshrrev_b32_e32 v206, 3, v201
	v_lshl_or_b32 v207, v206, 11, v200
	v_add_u32_e32 v206, 0x10000, v207
	v_add_u32_e32 v205, 0x20000, v207
	v_add_u32_e32 v204, 0x30000, v207
	v_add_u32_e32 v203, 0x40000, v207
	v_add_u32_e32 v202, 0x50000, v207
	s_lshr_b32 s83, s35, 6
	s_and_b32 s84, s35, 63
	s_mov_b32 s79, 0
	s_mul_i32 s84, s84, 0x60000
	s_lshl_b32 s83, s83, 18
	s_waitcnt lgkmcnt(0)
	s_add_u32 s66, s66, s84
	s_addc_u32 s67, s67, 0
	s_add_u32 s68, s68, s83
	s_addc_u32 s69, s69, 0
	s_add_u32 s83, s79, 0
	s_and_b32 s83, s83, 15
	s_lshl_b32 s83, s83, 7
	s_add_u32 s70, s66, s83
	s_addc_u32 s71, s67, 0
	s_add_u32 s72, s68, s83
	s_addc_u32 s73, s69, 0
	s_add_u32 s81, s80, 0x0
	s_add_u32 s82, s80, 0xc000
	s_add_u32 m0, s81, 0x0
	s_nop 0
	global_load_lds_dwordx4 v207, s[70:71]
	s_add_u32 m0, s81, 0x1000
	s_nop 0
	global_load_lds_dwordx4 v206, s[70:71]
	s_add_u32 m0, s81, 0x2000
	s_nop 0
	global_load_lds_dwordx4 v205, s[70:71]
	s_add_u32 m0, s81, 0x3000
	s_nop 0
	global_load_lds_dwordx4 v204, s[70:71]
	s_add_u32 m0, s81, 0x4000
	s_nop 0
	global_load_lds_dwordx4 v203, s[70:71]
	s_add_u32 m0, s81, 0x5000
	s_nop 0
	global_load_lds_dwordx4 v202, s[70:71]
	s_add_u32 m0, s82, 0x0
	s_nop 0
	global_load_lds_dwordx4 v207, s[72:73]
	s_add_u32 m0, s82, 0x1000
	s_nop 0
	global_load_lds_dwordx4 v206, s[72:73]
	s_add_u32 m0, s82, 0x2000
	s_nop 0
	global_load_lds_dwordx4 v205, s[72:73]
	s_add_u32 m0, s82, 0x3000
	s_nop 0
	global_load_lds_dwordx4 v204, s[72:73]
	s_add_u32 s83, s79, 1
	s_and_b32 s83, s83, 15
	s_lshl_b32 s83, s83, 7
	s_add_u32 s70, s66, s83
	s_addc_u32 s71, s67, 0
	s_add_u32 s72, s68, s83
	s_addc_u32 s73, s69, 0
	s_add_u32 s81, s80, 0x6000
	s_add_u32 s82, s80, 0x10000
	s_add_u32 m0, s81, 0x0
	s_nop 0
	global_load_lds_dwordx4 v207, s[70:71]
	s_add_u32 m0, s81, 0x1000
	s_nop 0
	global_load_lds_dwordx4 v206, s[70:71]
	s_add_u32 m0, s81, 0x2000
	s_nop 0
	global_load_lds_dwordx4 v205, s[70:71]
	s_add_u32 m0, s81, 0x3000
	s_nop 0
	global_load_lds_dwordx4 v204, s[70:71]
	s_add_u32 m0, s81, 0x4000
	s_nop 0
	global_load_lds_dwordx4 v203, s[70:71]
	v_mov_b32_e32 v2, 0
	v_mov_b32_e32 v3, 0
	v_mov_b32_e32 v4, 0
	v_mov_b32_e32 v5, 0
	v_mov_b32_e32 v6, 0
	v_mov_b32_e32 v7, 0
	v_mov_b32_e32 v8, 0
	v_mov_b32_e32 v9, 0
	v_mov_b32_e32 v10, 0
	v_mov_b32_e32 v11, 0
	v_mov_b32_e32 v12, 0
	v_mov_b32_e32 v13, 0
	v_mov_b32_e32 v14, 0
	v_mov_b32_e32 v15, 0
	v_mov_b32_e32 v16, 0
	v_mov_b32_e32 v17, 0
	v_mov_b32_e32 v18, 0
	v_mov_b32_e32 v19, 0
	v_mov_b32_e32 v20, 0
	v_mov_b32_e32 v21, 0
	v_mov_b32_e32 v22, 0
	v_mov_b32_e32 v23, 0
	v_mov_b32_e32 v24, 0
	v_mov_b32_e32 v25, 0
	v_mov_b32_e32 v26, 0
	v_mov_b32_e32 v27, 0
	v_mov_b32_e32 v28, 0
	v_mov_b32_e32 v29, 0
	v_mov_b32_e32 v30, 0
	v_mov_b32_e32 v31, 0
	v_mov_b32_e32 v32, 0
	v_mov_b32_e32 v33, 0
	v_mov_b32_e32 v34, 0
	v_mov_b32_e32 v35, 0
	v_mov_b32_e32 v36, 0
	v_mov_b32_e32 v37, 0
	v_mov_b32_e32 v38, 0
	v_mov_b32_e32 v39, 0
	v_mov_b32_e32 v40, 0
	v_mov_b32_e32 v41, 0
	v_mov_b32_e32 v42, 0
	v_mov_b32_e32 v43, 0
	v_mov_b32_e32 v44, 0
	v_mov_b32_e32 v45, 0
	v_mov_b32_e32 v46, 0
	v_mov_b32_e32 v47, 0
	v_mov_b32_e32 v48, 0
	v_mov_b32_e32 v49, 0
	v_mov_b32_e32 v50, 0
	v_mov_b32_e32 v51, 0
	v_mov_b32_e32 v52, 0
	v_mov_b32_e32 v53, 0
	v_mov_b32_e32 v54, 0
	v_mov_b32_e32 v55, 0
	v_mov_b32_e32 v56, 0
	v_mov_b32_e32 v57, 0
	v_mov_b32_e32 v58, 0
	v_mov_b32_e32 v59, 0
	v_mov_b32_e32 v60, 0
	v_mov_b32_e32 v61, 0
	v_mov_b32_e32 v62, 0
	v_mov_b32_e32 v63, 0
	v_mov_b32_e32 v64, 0
	v_mov_b32_e32 v65, 0
	v_mov_b32_e32 v66, 0
	v_mov_b32_e32 v67, 0
	v_mov_b32_e32 v68, 0
	v_mov_b32_e32 v69, 0
	v_mov_b32_e32 v70, 0
	v_mov_b32_e32 v71, 0
	v_mov_b32_e32 v72, 0
	v_mov_b32_e32 v73, 0
	v_mov_b32_e32 v74, 0
	v_mov_b32_e32 v75, 0
	v_mov_b32_e32 v76, 0
	v_mov_b32_e32 v77, 0
	v_mov_b32_e32 v78, 0
	v_mov_b32_e32 v79, 0
	v_mov_b32_e32 v80, 0
	v_mov_b32_e32 v81, 0
	v_mov_b32_e32 v82, 0
	v_mov_b32_e32 v83, 0
	v_mov_b32_e32 v84, 0
	v_mov_b32_e32 v85, 0
	v_mov_b32_e32 v86, 0
	v_mov_b32_e32 v87, 0
	v_mov_b32_e32 v88, 0
	v_mov_b32_e32 v89, 0
	v_mov_b32_e32 v90, 0
	v_mov_b32_e32 v91, 0
	v_mov_b32_e32 v92, 0
	v_mov_b32_e32 v93, 0
	v_mov_b32_e32 v94, 0
	v_mov_b32_e32 v95, 0
	v_mov_b32_e32 v96, 0
	v_mov_b32_e32 v97, 0
	s_waitcnt vmcnt(5)
	s_barrier
	ds_read_b128 v[240:243], v211 offset:0
	ds_read_b128 v[252:255], v215 offset:0
	ds_read_b128 v[236:239], v211 offset:4096
	ds_read_b128 v[248:251], v215 offset:4096
	ds_read_b128 v[244:247], v215 offset:8192
	s_mov_b32 s78, 0

.Lgm_ph5_noprio:
	s_barrier
	s_load_dwordx2 s[66:67], s[0:1], 0x118
	s_load_dwordx2 s[68:69], s[0:1], 0xd0
	v_and_b32_e32 v201, 0x3ff, v0
	v_readfirstlane_b32 s80, v0
	v_and_b32_e32 v200, 31, v201
	v_bfe_u32 v214, v201, 1, 3
	v_bfe_u32 v213, v201, 5, 1
	v_xor_b32_e32 v214, v214, v213
	v_lshlrev_b32_e32 v214, 4, v214
	s_and_b32 s80, s80, 0x3ff
	s_lshr_b32 s83, s80, 6
	s_lshl_b32 s80, s80, 4
	s_lshr_b32 s84, s83, 1
	s_and_b32 s83, s83, 1
	s_mul_i32 s84, s84, 0x3000
	s_lshl_b32 s83, s83, 13
	s_add_u32 s83, s83, 0xc000
	v_lshlrev_b32_e32 v200, 7, v200
	v_or_b32_e32 v200, v200, v214
	v_add_u32_e32 v215, s84, v200
	v_add_u32_e32 v211, s83, v200
	v_xor_b32_e32 v214, 0x20, v215
	v_xor_b32_e32 v210, 0x20, v211
	v_xor_b32_e32 v213, 0x40, v215
	v_xor_b32_e32 v209, 0x40, v211
	v_xor_b32_e32 v212, 0x60, v215
	v_xor_b32_e32 v208, 0x60, v211
	v_bfe_u32 v200, v201, 4, 3
	v_and_b32_e32 v206, 7, v201
	v_xor_b32_e32 v200, v200, v206
	v_lshlrev_b32_e32 v200, 4, v200
	v_lshrrev_b32_e32 v206, 3, v201
	v_lshl_or_b32 v207, v206, 11, v200
	v_add_u32_e32 v206, 0x10000, v207
	v_add_u32_e32 v205, 0x20000, v207
	v_add_u32_e32 v204, 0x30000, v207
	v_add_u32_e32 v203, 0x40000, v207
	v_add_u32_e32 v202, 0x50000, v207
	s_lshr_b32 s83, s28, 6
	s_and_b32 s84, s28, 63
	s_mov_b32 s79, 0
	s_mul_i32 s84, s84, 0x60000
	s_lshl_b32 s83, s83, 18
	s_waitcnt lgkmcnt(0)
	s_add_u32 s66, s66, s84
	s_addc_u32 s67, s67, 0
	s_add_u32 s68, s68, s83
	s_addc_u32 s69, s69, 0
	s_add_u32 s83, s79, 0
	s_and_b32 s83, s83, 15
	s_lshl_b32 s83, s83, 7
	s_add_u32 s70, s66, s83
	s_addc_u32 s71, s67, 0
	s_add_u32 s72, s68, s83
	s_addc_u32 s73, s69, 0
	s_add_u32 s81, s80, 0x0
	s_add_u32 s82, s80, 0xc000
	s_add_u32 m0, s81, 0x0
	s_nop 0
	global_load_lds_dwordx4 v207, s[70:71]
	s_add_u32 m0, s81, 0x1000
	s_nop 0
	global_load_lds_dwordx4 v206, s[70:71]
	s_add_u32 m0, s81, 0x2000
	s_nop 0
	global_load_lds_dwordx4 v205, s[70:71]
	s_add_u32 m0, s81, 0x3000
	s_nop 0
	global_load_lds_dwordx4 v204, s[70:71]
	s_add_u32 m0, s81, 0x4000
	s_nop 0
	global_load_lds_dwordx4 v203, s[70:71]
	s_add_u32 m0, s81, 0x5000
	s_nop 0
	global_load_lds_dwordx4 v202, s[70:71]
	s_add_u32 m0, s82, 0x0
	s_nop 0
	global_load_lds_dwordx4 v207, s[72:73]
	s_add_u32 m0, s82, 0x1000
	s_nop 0
	global_load_lds_dwordx4 v206, s[72:73]
	s_add_u32 m0, s82, 0x2000
	s_nop 0
	global_load_lds_dwordx4 v205, s[72:73]
	s_add_u32 m0, s82, 0x3000
	s_nop 0
	global_load_lds_dwordx4 v204, s[72:73]
	s_add_u32 s83, s79, 1
	s_and_b32 s83, s83, 15
	s_lshl_b32 s83, s83, 7
	s_add_u32 s70, s66, s83
	s_addc_u32 s71, s67, 0
	s_add_u32 s72, s68, s83
	s_addc_u32 s73, s69, 0
	s_add_u32 s81, s80, 0x6000
	s_add_u32 s82, s80, 0x10000
	s_add_u32 m0, s81, 0x0
	s_nop 0
	global_load_lds_dwordx4 v207, s[70:71]
	s_add_u32 m0, s81, 0x1000
	s_nop 0
	global_load_lds_dwordx4 v206, s[70:71]
	s_add_u32 m0, s81, 0x2000
	s_nop 0
	global_load_lds_dwordx4 v205, s[70:71]
	s_add_u32 m0, s81, 0x3000
	s_nop 0
	global_load_lds_dwordx4 v204, s[70:71]
	s_add_u32 m0, s81, 0x4000
	s_nop 0
	global_load_lds_dwordx4 v203, s[70:71]
	v_mov_b32_e32 v2, 0
	v_mov_b32_e32 v3, 0
	v_mov_b32_e32 v4, 0
	v_mov_b32_e32 v5, 0
	v_mov_b32_e32 v6, 0
	v_mov_b32_e32 v7, 0
	v_mov_b32_e32 v8, 0
	v_mov_b32_e32 v9, 0
	v_mov_b32_e32 v10, 0
	v_mov_b32_e32 v11, 0
	v_mov_b32_e32 v12, 0
	v_mov_b32_e32 v13, 0
	v_mov_b32_e32 v14, 0
	v_mov_b32_e32 v15, 0
	v_mov_b32_e32 v16, 0
	v_mov_b32_e32 v17, 0
	v_mov_b32_e32 v18, 0
	v_mov_b32_e32 v19, 0
	v_mov_b32_e32 v20, 0
	v_mov_b32_e32 v21, 0
	v_mov_b32_e32 v22, 0
	v_mov_b32_e32 v23, 0
	v_mov_b32_e32 v24, 0
	v_mov_b32_e32 v25, 0
	v_mov_b32_e32 v26, 0
	v_mov_b32_e32 v27, 0
	v_mov_b32_e32 v28, 0
	v_mov_b32_e32 v29, 0
	v_mov_b32_e32 v30, 0
	v_mov_b32_e32 v31, 0
	v_mov_b32_e32 v32, 0
	v_mov_b32_e32 v33, 0
	v_mov_b32_e32 v34, 0
	v_mov_b32_e32 v35, 0
	v_mov_b32_e32 v36, 0
	v_mov_b32_e32 v37, 0
	v_mov_b32_e32 v38, 0
	v_mov_b32_e32 v39, 0
	v_mov_b32_e32 v40, 0
	v_mov_b32_e32 v41, 0
	v_mov_b32_e32 v42, 0
	v_mov_b32_e32 v43, 0
	v_mov_b32_e32 v44, 0
	v_mov_b32_e32 v45, 0
	v_mov_b32_e32 v46, 0
	v_mov_b32_e32 v47, 0
	v_mov_b32_e32 v48, 0
	v_mov_b32_e32 v49, 0
	v_mov_b32_e32 v50, 0
	v_mov_b32_e32 v51, 0
	v_mov_b32_e32 v52, 0
	v_mov_b32_e32 v53, 0
	v_mov_b32_e32 v54, 0
	v_mov_b32_e32 v55, 0
	v_mov_b32_e32 v56, 0
	v_mov_b32_e32 v57, 0
	v_mov_b32_e32 v58, 0
	v_mov_b32_e32 v59, 0
	v_mov_b32_e32 v60, 0
	v_mov_b32_e32 v61, 0
	v_mov_b32_e32 v62, 0
	v_mov_b32_e32 v63, 0
	v_mov_b32_e32 v64, 0
	v_mov_b32_e32 v65, 0
	v_mov_b32_e32 v66, 0
	v_mov_b32_e32 v67, 0
	v_mov_b32_e32 v68, 0
	v_mov_b32_e32 v69, 0
	v_mov_b32_e32 v70, 0
	v_mov_b32_e32 v71, 0
	v_mov_b32_e32 v72, 0
	v_mov_b32_e32 v73, 0
	v_mov_b32_e32 v74, 0
	v_mov_b32_e32 v75, 0
	v_mov_b32_e32 v76, 0
	v_mov_b32_e32 v77, 0
	v_mov_b32_e32 v78, 0
	v_mov_b32_e32 v79, 0
	v_mov_b32_e32 v80, 0
	v_mov_b32_e32 v81, 0
	v_mov_b32_e32 v82, 0
	v_mov_b32_e32 v83, 0
	v_mov_b32_e32 v84, 0
	v_mov_b32_e32 v85, 0
	v_mov_b32_e32 v86, 0
	v_mov_b32_e32 v87, 0
	v_mov_b32_e32 v88, 0
	v_mov_b32_e32 v89, 0
	v_mov_b32_e32 v90, 0
	v_mov_b32_e32 v91, 0
	v_mov_b32_e32 v92, 0
	v_mov_b32_e32 v93, 0
	v_mov_b32_e32 v94, 0
	v_mov_b32_e32 v95, 0
	v_mov_b32_e32 v96, 0
	v_mov_b32_e32 v97, 0
	s_waitcnt vmcnt(5)
	s_barrier
	ds_read_b128 v[240:243], v211 offset:0
	ds_read_b128 v[252:255], v215 offset:0
	ds_read_b128 v[236:239], v211 offset:4096
	ds_read_b128 v[248:251], v215 offset:4096
	ds_read_b128 v[244:247], v215 offset:8192
	s_mov_b32 s78, 0

.Lgm_ph7_noprio:
	s_barrier
	s_load_dwordx2 s[66:67], s[0:1], 0x90
	s_load_dwordx2 s[68:69], s[0:1], 0xd8
	v_and_b32_e32 v201, 0x3ff, v0
	v_readfirstlane_b32 s80, v0
	v_and_b32_e32 v200, 31, v201
	v_bfe_u32 v214, v201, 1, 3
	v_bfe_u32 v213, v201, 5, 1
	v_xor_b32_e32 v214, v214, v213
	v_lshlrev_b32_e32 v214, 4, v214
	s_and_b32 s80, s80, 0x3ff
	s_lshr_b32 s83, s80, 6
	s_lshl_b32 s80, s80, 4
	s_lshr_b32 s84, s83, 1
	s_and_b32 s83, s83, 1
	s_mul_i32 s84, s84, 0x3000
	s_lshl_b32 s83, s83, 13
	s_add_u32 s83, s83, 0xc000
	v_lshlrev_b32_e32 v200, 7, v200
	v_or_b32_e32 v200, v200, v214
	v_add_u32_e32 v215, s84, v200
	v_add_u32_e32 v211, s83, v200
	v_xor_b32_e32 v214, 0x20, v215
	v_xor_b32_e32 v210, 0x20, v211
	v_xor_b32_e32 v213, 0x40, v215
	v_xor_b32_e32 v209, 0x40, v211
	v_xor_b32_e32 v212, 0x60, v215
	v_xor_b32_e32 v208, 0x60, v211
	v_bfe_u32 v200, v201, 4, 3
	v_and_b32_e32 v206, 7, v201
	v_xor_b32_e32 v200, v200, v206
	v_lshlrev_b32_e32 v200, 4, v200
	v_lshrrev_b32_e32 v206, 3, v201
	v_lshl_or_b32 v207, v206, 11, v200
	v_add_u32_e32 v206, 0x10000, v207
	v_add_u32_e32 v205, 0x20000, v207
	v_add_u32_e32 v204, 0x30000, v207
	v_add_u32_e32 v203, 0x40000, v207
	v_add_u32_e32 v202, 0x50000, v207
	s_lshr_b32 s83, s56, 6
	s_and_b32 s84, s56, 63
	s_mov_b32 s79, 0
	s_mul_i32 s84, s84, 0x60000
	s_lshl_b32 s83, s83, 18
	s_waitcnt lgkmcnt(0)
	s_add_u32 s66, s66, s84
	s_addc_u32 s67, s67, 0
	s_add_u32 s68, s68, s83
	s_addc_u32 s69, s69, 0
	s_add_u32 s83, s79, 0
	s_and_b32 s83, s83, 15
	s_lshl_b32 s83, s83, 7
	s_add_u32 s70, s66, s83
	s_addc_u32 s71, s67, 0
	s_add_u32 s72, s68, s83
	s_addc_u32 s73, s69, 0
	s_add_u32 s81, s80, 0x0
	s_add_u32 s82, s80, 0xc000
	s_add_u32 m0, s81, 0x0
	s_nop 0
	global_load_lds_dwordx4 v207, s[70:71]
	s_add_u32 m0, s81, 0x1000
	s_nop 0
	global_load_lds_dwordx4 v206, s[70:71]
	s_add_u32 m0, s81, 0x2000
	s_nop 0
	global_load_lds_dwordx4 v205, s[70:71]
	s_add_u32 m0, s81, 0x3000
	s_nop 0
	global_load_lds_dwordx4 v204, s[70:71]
	s_add_u32 m0, s81, 0x4000
	s_nop 0
	global_load_lds_dwordx4 v203, s[70:71]
	s_add_u32 m0, s81, 0x5000
	s_nop 0
	global_load_lds_dwordx4 v202, s[70:71]
	s_add_u32 m0, s82, 0x0
	s_nop 0
	global_load_lds_dwordx4 v207, s[72:73]
	s_add_u32 m0, s82, 0x1000
	s_nop 0
	global_load_lds_dwordx4 v206, s[72:73]
	s_add_u32 m0, s82, 0x2000
	s_nop 0
	global_load_lds_dwordx4 v205, s[72:73]
	s_add_u32 m0, s82, 0x3000
	s_nop 0
	global_load_lds_dwordx4 v204, s[72:73]
	s_add_u32 s83, s79, 1
	s_and_b32 s83, s83, 15
	s_lshl_b32 s83, s83, 7
	s_add_u32 s70, s66, s83
	s_addc_u32 s71, s67, 0
	s_add_u32 s72, s68, s83
	s_addc_u32 s73, s69, 0
	s_add_u32 s81, s80, 0x6000
	s_add_u32 s82, s80, 0x10000
	s_add_u32 m0, s81, 0x0
	s_nop 0
	global_load_lds_dwordx4 v207, s[70:71]
	s_add_u32 m0, s81, 0x1000
	s_nop 0
	global_load_lds_dwordx4 v206, s[70:71]
	s_add_u32 m0, s81, 0x2000
	s_nop 0
	global_load_lds_dwordx4 v205, s[70:71]
	s_add_u32 m0, s81, 0x3000
	s_nop 0
	global_load_lds_dwordx4 v204, s[70:71]
	s_add_u32 m0, s81, 0x4000
	s_nop 0
	global_load_lds_dwordx4 v203, s[70:71]
	v_mov_b32_e32 v2, 0
	v_mov_b32_e32 v3, 0
	v_mov_b32_e32 v4, 0
	v_mov_b32_e32 v5, 0
	v_mov_b32_e32 v6, 0
	v_mov_b32_e32 v7, 0
	v_mov_b32_e32 v8, 0
	v_mov_b32_e32 v9, 0
	v_mov_b32_e32 v10, 0
	v_mov_b32_e32 v11, 0
	v_mov_b32_e32 v12, 0
	v_mov_b32_e32 v13, 0
	v_mov_b32_e32 v14, 0
	v_mov_b32_e32 v15, 0
	v_mov_b32_e32 v16, 0
	v_mov_b32_e32 v17, 0
	v_mov_b32_e32 v18, 0
	v_mov_b32_e32 v19, 0
	v_mov_b32_e32 v20, 0
	v_mov_b32_e32 v21, 0
	v_mov_b32_e32 v22, 0
	v_mov_b32_e32 v23, 0
	v_mov_b32_e32 v24, 0
	v_mov_b32_e32 v25, 0
	v_mov_b32_e32 v26, 0
	v_mov_b32_e32 v27, 0
	v_mov_b32_e32 v28, 0
	v_mov_b32_e32 v29, 0
	v_mov_b32_e32 v30, 0
	v_mov_b32_e32 v31, 0
	v_mov_b32_e32 v32, 0
	v_mov_b32_e32 v33, 0
	v_mov_b32_e32 v34, 0
	v_mov_b32_e32 v35, 0
	v_mov_b32_e32 v36, 0
	v_mov_b32_e32 v37, 0
	v_mov_b32_e32 v38, 0
	v_mov_b32_e32 v39, 0
	v_mov_b32_e32 v40, 0
	v_mov_b32_e32 v41, 0
	v_mov_b32_e32 v42, 0
	v_mov_b32_e32 v43, 0
	v_mov_b32_e32 v44, 0
	v_mov_b32_e32 v45, 0
	v_mov_b32_e32 v46, 0
	v_mov_b32_e32 v47, 0
	v_mov_b32_e32 v48, 0
	v_mov_b32_e32 v49, 0
	v_mov_b32_e32 v50, 0
	v_mov_b32_e32 v51, 0
	v_mov_b32_e32 v52, 0
	v_mov_b32_e32 v53, 0
	v_mov_b32_e32 v54, 0
	v_mov_b32_e32 v55, 0
	v_mov_b32_e32 v56, 0
	v_mov_b32_e32 v57, 0
	v_mov_b32_e32 v58, 0
	v_mov_b32_e32 v59, 0
	v_mov_b32_e32 v60, 0
	v_mov_b32_e32 v61, 0
	v_mov_b32_e32 v62, 0
	v_mov_b32_e32 v63, 0
	v_mov_b32_e32 v64, 0
	v_mov_b32_e32 v65, 0
	v_mov_b32_e32 v66, 0
	v_mov_b32_e32 v67, 0
	v_mov_b32_e32 v68, 0
	v_mov_b32_e32 v69, 0
	v_mov_b32_e32 v70, 0
	v_mov_b32_e32 v71, 0
	v_mov_b32_e32 v72, 0
	v_mov_b32_e32 v73, 0
	v_mov_b32_e32 v74, 0
	v_mov_b32_e32 v75, 0
	v_mov_b32_e32 v76, 0
	v_mov_b32_e32 v77, 0
	v_mov_b32_e32 v78, 0
	v_mov_b32_e32 v79, 0
	v_mov_b32_e32 v80, 0
	v_mov_b32_e32 v81, 0
	v_mov_b32_e32 v82, 0
	v_mov_b32_e32 v83, 0
	v_mov_b32_e32 v84, 0
	v_mov_b32_e32 v85, 0
	v_mov_b32_e32 v86, 0
	v_mov_b32_e32 v87, 0
	v_mov_b32_e32 v88, 0
	v_mov_b32_e32 v89, 0
	v_mov_b32_e32 v90, 0
	v_mov_b32_e32 v91, 0
	v_mov_b32_e32 v92, 0
	v_mov_b32_e32 v93, 0
	v_mov_b32_e32 v94, 0
	v_mov_b32_e32 v95, 0
	v_mov_b32_e32 v96, 0
	v_mov_b32_e32 v97, 0
	s_waitcnt vmcnt(5)
	s_barrier
	ds_read_b128 v[240:243], v211 offset:0
	ds_read_b128 v[252:255], v215 offset:0
	ds_read_b128 v[236:239], v211 offset:4096
	ds_read_b128 v[248:251], v215 offset:4096
	ds_read_b128 v[244:247], v215 offset:8192
	s_mov_b32 s78, 0

.Lgm_ph11_noprio:
	s_barrier
	s_load_dwordx2 s[66:67], s[0:1], 0x128
	s_load_dwordx2 s[68:69], s[0:1], 0xf0
	v_and_b32_e32 v201, 0x3ff, v0
	v_readfirstlane_b32 s80, v0
	v_and_b32_e32 v200, 31, v201
	v_bfe_u32 v214, v201, 1, 3
	v_bfe_u32 v213, v201, 5, 1
	v_xor_b32_e32 v214, v214, v213
	v_lshlrev_b32_e32 v214, 4, v214
	s_and_b32 s80, s80, 0x3ff
	s_lshr_b32 s83, s80, 6
	s_lshl_b32 s80, s80, 4
	s_lshr_b32 s84, s83, 1
	s_and_b32 s83, s83, 1
	s_mul_i32 s84, s84, 0x3000
	s_lshl_b32 s83, s83, 13
	s_add_u32 s83, s83, 0xc000
	v_lshlrev_b32_e32 v200, 7, v200
	v_or_b32_e32 v200, v200, v214
	v_add_u32_e32 v215, s84, v200
	v_add_u32_e32 v211, s83, v200
	v_xor_b32_e32 v214, 0x20, v215
	v_xor_b32_e32 v210, 0x20, v211
	v_xor_b32_e32 v213, 0x40, v215
	v_xor_b32_e32 v209, 0x40, v211
	v_xor_b32_e32 v212, 0x60, v215
	v_xor_b32_e32 v208, 0x60, v211
	v_bfe_u32 v200, v201, 4, 3
	v_and_b32_e32 v206, 7, v201
	v_xor_b32_e32 v200, v200, v206
	v_lshlrev_b32_e32 v200, 4, v200
	v_lshrrev_b32_e32 v206, 3, v201
	v_lshl_or_b32 v207, v206, 11, v200
	v_add_u32_e32 v206, 0x10000, v207
	v_add_u32_e32 v205, 0x20000, v207
	v_add_u32_e32 v204, 0x30000, v207
	v_add_u32_e32 v203, 0x40000, v207
	v_add_u32_e32 v202, 0x50000, v207
	s_lshr_b32 s83, s28, 6
	s_and_b32 s84, s28, 63
	s_mov_b32 s79, 0
	s_mul_i32 s84, s84, 0x60000
	s_lshl_b32 s83, s83, 18
	s_waitcnt lgkmcnt(0)
	s_add_u32 s66, s66, s84
	s_addc_u32 s67, s67, 0
	s_add_u32 s68, s68, s83
	s_addc_u32 s69, s69, 0
	s_add_u32 s83, s79, 0
	s_and_b32 s83, s83, 15
	s_lshl_b32 s83, s83, 7
	s_add_u32 s70, s66, s83
	s_addc_u32 s71, s67, 0
	s_add_u32 s72, s68, s83
	s_addc_u32 s73, s69, 0
	s_add_u32 s81, s80, 0x0
	s_add_u32 s82, s80, 0xc000
	s_add_u32 m0, s81, 0x0
	s_nop 0
	global_load_lds_dwordx4 v207, s[70:71]
	s_add_u32 m0, s81, 0x1000
	s_nop 0
	global_load_lds_dwordx4 v206, s[70:71]
	s_add_u32 m0, s81, 0x2000
	s_nop 0
	global_load_lds_dwordx4 v205, s[70:71]
	s_add_u32 m0, s81, 0x3000
	s_nop 0
	global_load_lds_dwordx4 v204, s[70:71]
	s_add_u32 m0, s81, 0x4000
	s_nop 0
	global_load_lds_dwordx4 v203, s[70:71]
	s_add_u32 m0, s81, 0x5000
	s_nop 0
	global_load_lds_dwordx4 v202, s[70:71]
	s_add_u32 m0, s82, 0x0
	s_nop 0
	global_load_lds_dwordx4 v207, s[72:73]
	s_add_u32 m0, s82, 0x1000
	s_nop 0
	global_load_lds_dwordx4 v206, s[72:73]
	s_add_u32 m0, s82, 0x2000
	s_nop 0
	global_load_lds_dwordx4 v205, s[72:73]
	s_add_u32 m0, s82, 0x3000
	s_nop 0
	global_load_lds_dwordx4 v204, s[72:73]
	s_add_u32 s83, s79, 1
	s_and_b32 s83, s83, 15
	s_lshl_b32 s83, s83, 7
	s_add_u32 s70, s66, s83
	s_addc_u32 s71, s67, 0
	s_add_u32 s72, s68, s83
	s_addc_u32 s73, s69, 0
	s_add_u32 s81, s80, 0x6000
	s_add_u32 s82, s80, 0x10000
	s_add_u32 m0, s81, 0x0
	s_nop 0
	global_load_lds_dwordx4 v207, s[70:71]
	s_add_u32 m0, s81, 0x1000
	s_nop 0
	global_load_lds_dwordx4 v206, s[70:71]
	s_add_u32 m0, s81, 0x2000
	s_nop 0
	global_load_lds_dwordx4 v205, s[70:71]
	s_add_u32 m0, s81, 0x3000
	s_nop 0
	global_load_lds_dwordx4 v204, s[70:71]
	s_add_u32 m0, s81, 0x4000
	s_nop 0
	global_load_lds_dwordx4 v203, s[70:71]
	v_mov_b32_e32 v2, 0
	v_mov_b32_e32 v3, 0
	v_mov_b32_e32 v4, 0
	v_mov_b32_e32 v5, 0
	v_mov_b32_e32 v6, 0
	v_mov_b32_e32 v7, 0
	v_mov_b32_e32 v8, 0
	v_mov_b32_e32 v9, 0
	v_mov_b32_e32 v10, 0
	v_mov_b32_e32 v11, 0
	v_mov_b32_e32 v12, 0
	v_mov_b32_e32 v13, 0
	v_mov_b32_e32 v14, 0
	v_mov_b32_e32 v15, 0
	v_mov_b32_e32 v16, 0
	v_mov_b32_e32 v17, 0
	v_mov_b32_e32 v18, 0
	v_mov_b32_e32 v19, 0
	v_mov_b32_e32 v20, 0
	v_mov_b32_e32 v21, 0
	v_mov_b32_e32 v22, 0
	v_mov_b32_e32 v23, 0
	v_mov_b32_e32 v24, 0
	v_mov_b32_e32 v25, 0
	v_mov_b32_e32 v26, 0
	v_mov_b32_e32 v27, 0
	v_mov_b32_e32 v28, 0
	v_mov_b32_e32 v29, 0
	v_mov_b32_e32 v30, 0
	v_mov_b32_e32 v31, 0
	v_mov_b32_e32 v32, 0
	v_mov_b32_e32 v33, 0
	v_mov_b32_e32 v34, 0
	v_mov_b32_e32 v35, 0
	v_mov_b32_e32 v36, 0
	v_mov_b32_e32 v37, 0
	v_mov_b32_e32 v38, 0
	v_mov_b32_e32 v39, 0
	v_mov_b32_e32 v40, 0
	v_mov_b32_e32 v41, 0
	v_mov_b32_e32 v42, 0
	v_mov_b32_e32 v43, 0
	v_mov_b32_e32 v44, 0
	v_mov_b32_e32 v45, 0
	v_mov_b32_e32 v46, 0
	v_mov_b32_e32 v47, 0
	v_mov_b32_e32 v48, 0
	v_mov_b32_e32 v49, 0
	v_mov_b32_e32 v50, 0
	v_mov_b32_e32 v51, 0
	v_mov_b32_e32 v52, 0
	v_mov_b32_e32 v53, 0
	v_mov_b32_e32 v54, 0
	v_mov_b32_e32 v55, 0
	v_mov_b32_e32 v56, 0
	v_mov_b32_e32 v57, 0
	v_mov_b32_e32 v58, 0
	v_mov_b32_e32 v59, 0
	v_mov_b32_e32 v60, 0
	v_mov_b32_e32 v61, 0
	v_mov_b32_e32 v62, 0
	v_mov_b32_e32 v63, 0
	v_mov_b32_e32 v64, 0
	v_mov_b32_e32 v65, 0
	v_mov_b32_e32 v66, 0
	v_mov_b32_e32 v67, 0
	v_mov_b32_e32 v68, 0
	v_mov_b32_e32 v69, 0
	v_mov_b32_e32 v70, 0
	v_mov_b32_e32 v71, 0
	v_mov_b32_e32 v72, 0
	v_mov_b32_e32 v73, 0
	v_mov_b32_e32 v74, 0
	v_mov_b32_e32 v75, 0
	v_mov_b32_e32 v76, 0
	v_mov_b32_e32 v77, 0
	v_mov_b32_e32 v78, 0
	v_mov_b32_e32 v79, 0
	v_mov_b32_e32 v80, 0
	v_mov_b32_e32 v81, 0
	v_mov_b32_e32 v82, 0
	v_mov_b32_e32 v83, 0
	v_mov_b32_e32 v84, 0
	v_mov_b32_e32 v85, 0
	v_mov_b32_e32 v86, 0
	v_mov_b32_e32 v87, 0
	v_mov_b32_e32 v88, 0
	v_mov_b32_e32 v89, 0
	v_mov_b32_e32 v90, 0
	v_mov_b32_e32 v91, 0
	v_mov_b32_e32 v92, 0
	v_mov_b32_e32 v93, 0
	v_mov_b32_e32 v94, 0
	v_mov_b32_e32 v95, 0
	v_mov_b32_e32 v96, 0
	v_mov_b32_e32 v97, 0
	s_waitcnt vmcnt(5)
	s_barrier
	ds_read_b128 v[240:243], v211 offset:0
	ds_read_b128 v[252:255], v215 offset:0
	ds_read_b128 v[236:239], v211 offset:4096
	ds_read_b128 v[248:251], v215 offset:4096
	ds_read_b128 v[244:247], v215 offset:8192
	s_mov_b32 s78, 0

.Lgm_ph13_noprio:
	s_barrier
	s_load_dwordx2 s[66:67], s[0:1], 0x90
	s_load_dwordx2 s[68:69], s[0:1], 0xf8
	v_and_b32_e32 v201, 0x3ff, v0
	v_readfirstlane_b32 s80, v0
	v_and_b32_e32 v200, 31, v201
	v_bfe_u32 v214, v201, 1, 3
	v_bfe_u32 v213, v201, 5, 1
	v_xor_b32_e32 v214, v214, v213
	v_lshlrev_b32_e32 v214, 4, v214
	s_and_b32 s80, s80, 0x3ff
	s_lshr_b32 s83, s80, 6
	s_lshl_b32 s80, s80, 4
	s_lshr_b32 s84, s83, 1
	s_and_b32 s83, s83, 1
	s_mul_i32 s84, s84, 0x3000
	s_lshl_b32 s83, s83, 13
	s_add_u32 s83, s83, 0xc000
	v_lshlrev_b32_e32 v200, 7, v200
	v_or_b32_e32 v200, v200, v214
	v_add_u32_e32 v215, s84, v200
	v_add_u32_e32 v211, s83, v200
	v_xor_b32_e32 v214, 0x20, v215
	v_xor_b32_e32 v210, 0x20, v211
	v_xor_b32_e32 v213, 0x40, v215
	v_xor_b32_e32 v209, 0x40, v211
	v_xor_b32_e32 v212, 0x60, v215
	v_xor_b32_e32 v208, 0x60, v211
	v_bfe_u32 v200, v201, 4, 3
	v_and_b32_e32 v206, 7, v201
	v_xor_b32_e32 v200, v200, v206
	v_lshlrev_b32_e32 v200, 4, v200
	v_lshrrev_b32_e32 v206, 3, v201
	v_lshl_or_b32 v207, v206, 11, v200
	v_add_u32_e32 v206, 0x10000, v207
	v_add_u32_e32 v205, 0x20000, v207
	v_add_u32_e32 v204, 0x30000, v207
	v_add_u32_e32 v203, 0x40000, v207
	v_add_u32_e32 v202, 0x50000, v207
	s_lshr_b32 s83, s64, 6
	s_and_b32 s84, s64, 63
	s_mov_b32 s79, 0
	s_mul_i32 s84, s84, 0x60000
	s_lshl_b32 s83, s83, 18
	s_waitcnt lgkmcnt(0)
	s_add_u32 s66, s66, s84
	s_addc_u32 s67, s67, 0
	s_add_u32 s68, s68, s83
	s_addc_u32 s69, s69, 0
	s_add_u32 s83, s79, 0
	s_and_b32 s83, s83, 15
	s_lshl_b32 s83, s83, 7
	s_add_u32 s70, s66, s83
	s_addc_u32 s71, s67, 0
	s_add_u32 s72, s68, s83
	s_addc_u32 s73, s69, 0
	s_add_u32 s81, s80, 0x0
	s_add_u32 s82, s80, 0xc000
	s_add_u32 m0, s81, 0x0
	s_nop 0
	global_load_lds_dwordx4 v207, s[70:71]
	s_add_u32 m0, s81, 0x1000
	s_nop 0
	global_load_lds_dwordx4 v206, s[70:71]
	s_add_u32 m0, s81, 0x2000
	s_nop 0
	global_load_lds_dwordx4 v205, s[70:71]
	s_add_u32 m0, s81, 0x3000
	s_nop 0
	global_load_lds_dwordx4 v204, s[70:71]
	s_add_u32 m0, s81, 0x4000
	s_nop 0
	global_load_lds_dwordx4 v203, s[70:71]
	s_add_u32 m0, s81, 0x5000
	s_nop 0
	global_load_lds_dwordx4 v202, s[70:71]
	s_add_u32 m0, s82, 0x0
	s_nop 0
	global_load_lds_dwordx4 v207, s[72:73]
	s_add_u32 m0, s82, 0x1000
	s_nop 0
	global_load_lds_dwordx4 v206, s[72:73]
	s_add_u32 m0, s82, 0x2000
	s_nop 0
	global_load_lds_dwordx4 v205, s[72:73]
	s_add_u32 m0, s82, 0x3000
	s_nop 0
	global_load_lds_dwordx4 v204, s[72:73]
	s_add_u32 s83, s79, 1
	s_and_b32 s83, s83, 15
	s_lshl_b32 s83, s83, 7
	s_add_u32 s70, s66, s83
	s_addc_u32 s71, s67, 0
	s_add_u32 s72, s68, s83
	s_addc_u32 s73, s69, 0
	s_add_u32 s81, s80, 0x6000
	s_add_u32 s82, s80, 0x10000
	s_add_u32 m0, s81, 0x0
	s_nop 0
	global_load_lds_dwordx4 v207, s[70:71]
	s_add_u32 m0, s81, 0x1000
	s_nop 0
	global_load_lds_dwordx4 v206, s[70:71]
	s_add_u32 m0, s81, 0x2000
	s_nop 0
	global_load_lds_dwordx4 v205, s[70:71]
	s_add_u32 m0, s81, 0x3000
	s_nop 0
	global_load_lds_dwordx4 v204, s[70:71]
	s_add_u32 m0, s81, 0x4000
	s_nop 0
	global_load_lds_dwordx4 v203, s[70:71]
	v_mov_b32_e32 v2, 0
	v_mov_b32_e32 v3, 0
	v_mov_b32_e32 v4, 0
	v_mov_b32_e32 v5, 0
	v_mov_b32_e32 v6, 0
	v_mov_b32_e32 v7, 0
	v_mov_b32_e32 v8, 0
	v_mov_b32_e32 v9, 0
	v_mov_b32_e32 v10, 0
	v_mov_b32_e32 v11, 0
	v_mov_b32_e32 v12, 0
	v_mov_b32_e32 v13, 0
	v_mov_b32_e32 v14, 0
	v_mov_b32_e32 v15, 0
	v_mov_b32_e32 v16, 0
	v_mov_b32_e32 v17, 0
	v_mov_b32_e32 v18, 0
	v_mov_b32_e32 v19, 0
	v_mov_b32_e32 v20, 0
	v_mov_b32_e32 v21, 0
	v_mov_b32_e32 v22, 0
	v_mov_b32_e32 v23, 0
	v_mov_b32_e32 v24, 0
	v_mov_b32_e32 v25, 0
	v_mov_b32_e32 v26, 0
	v_mov_b32_e32 v27, 0
	v_mov_b32_e32 v28, 0
	v_mov_b32_e32 v29, 0
	v_mov_b32_e32 v30, 0
	v_mov_b32_e32 v31, 0
	v_mov_b32_e32 v32, 0
	v_mov_b32_e32 v33, 0
	v_mov_b32_e32 v34, 0
	v_mov_b32_e32 v35, 0
	v_mov_b32_e32 v36, 0
	v_mov_b32_e32 v37, 0
	v_mov_b32_e32 v38, 0
	v_mov_b32_e32 v39, 0
	v_mov_b32_e32 v40, 0
	v_mov_b32_e32 v41, 0
	v_mov_b32_e32 v42, 0
	v_mov_b32_e32 v43, 0
	v_mov_b32_e32 v44, 0
	v_mov_b32_e32 v45, 0
	v_mov_b32_e32 v46, 0
	v_mov_b32_e32 v47, 0
	v_mov_b32_e32 v48, 0
	v_mov_b32_e32 v49, 0
	v_mov_b32_e32 v50, 0
	v_mov_b32_e32 v51, 0
	v_mov_b32_e32 v52, 0
	v_mov_b32_e32 v53, 0
	v_mov_b32_e32 v54, 0
	v_mov_b32_e32 v55, 0
	v_mov_b32_e32 v56, 0
	v_mov_b32_e32 v57, 0
	v_mov_b32_e32 v58, 0
	v_mov_b32_e32 v59, 0
	v_mov_b32_e32 v60, 0
	v_mov_b32_e32 v61, 0
	v_mov_b32_e32 v62, 0
	v_mov_b32_e32 v63, 0
	v_mov_b32_e32 v64, 0
	v_mov_b32_e32 v65, 0
	v_mov_b32_e32 v66, 0
	v_mov_b32_e32 v67, 0
	v_mov_b32_e32 v68, 0
	v_mov_b32_e32 v69, 0
	v_mov_b32_e32 v70, 0
	v_mov_b32_e32 v71, 0
	v_mov_b32_e32 v72, 0
	v_mov_b32_e32 v73, 0
	v_mov_b32_e32 v74, 0
	v_mov_b32_e32 v75, 0
	v_mov_b32_e32 v76, 0
	v_mov_b32_e32 v77, 0
	v_mov_b32_e32 v78, 0
	v_mov_b32_e32 v79, 0
	v_mov_b32_e32 v80, 0
	v_mov_b32_e32 v81, 0
	v_mov_b32_e32 v82, 0
	v_mov_b32_e32 v83, 0
	v_mov_b32_e32 v84, 0
	v_mov_b32_e32 v85, 0
	v_mov_b32_e32 v86, 0
	v_mov_b32_e32 v87, 0
	v_mov_b32_e32 v88, 0
	v_mov_b32_e32 v89, 0
	v_mov_b32_e32 v90, 0
	v_mov_b32_e32 v91, 0
	v_mov_b32_e32 v92, 0
	v_mov_b32_e32 v93, 0
	v_mov_b32_e32 v94, 0
	v_mov_b32_e32 v95, 0
	v_mov_b32_e32 v96, 0
	v_mov_b32_e32 v97, 0
	s_waitcnt vmcnt(5)
	s_barrier
	ds_read_b128 v[240:243], v211 offset:0
	ds_read_b128 v[252:255], v215 offset:0
	ds_read_b128 v[236:239], v211 offset:4096
	ds_read_b128 v[248:251], v215 offset:4096
	ds_read_b128 v[244:247], v215 offset:8192
	s_mov_b32 s78, 0

.Lgm_ph15_noprio:
	s_barrier
	s_load_dwordx2 s[66:67], s[0:1], 0x178
	s_load_dwordx2 s[68:69], s[0:1], 0x100
	v_and_b32_e32 v201, 0x3ff, v0
	v_readfirstlane_b32 s80, v0
	v_and_b32_e32 v200, 31, v201
	v_bfe_u32 v214, v201, 1, 3
	v_bfe_u32 v213, v201, 5, 1
	v_xor_b32_e32 v214, v214, v213
	v_lshlrev_b32_e32 v214, 4, v214
	s_and_b32 s80, s80, 0x3ff
	s_lshr_b32 s83, s80, 6
	s_lshl_b32 s80, s80, 4
	s_lshr_b32 s84, s83, 1
	s_and_b32 s83, s83, 1
	s_mul_i32 s84, s84, 0x3000
	s_lshl_b32 s83, s83, 13
	s_add_u32 s83, s83, 0xc000
	v_lshlrev_b32_e32 v200, 7, v200
	v_or_b32_e32 v200, v200, v214
	v_add_u32_e32 v215, s84, v200
	v_add_u32_e32 v211, s83, v200
	v_xor_b32_e32 v214, 0x20, v215
	v_xor_b32_e32 v210, 0x20, v211
	v_xor_b32_e32 v213, 0x40, v215
	v_xor_b32_e32 v209, 0x40, v211
	v_xor_b32_e32 v212, 0x60, v215
	v_xor_b32_e32 v208, 0x60, v211
	v_bfe_u32 v200, v201, 4, 3
	v_and_b32_e32 v206, 7, v201
	v_xor_b32_e32 v200, v200, v206
	v_lshlrev_b32_e32 v200, 4, v200
	v_lshrrev_b32_e32 v206, 3, v201
	v_lshl_or_b32 v207, v206, 11, v200
	v_add_u32_e32 v206, 0x10000, v207
	v_add_u32_e32 v205, 0x20000, v207
	v_add_u32_e32 v204, 0x30000, v207
	v_add_u32_e32 v203, 0x40000, v207
	v_add_u32_e32 v202, 0x50000, v207
	s_lshr_b32 s83, s28, 6
	s_and_b32 s84, s28, 63
	s_mov_b32 s79, 0
	s_mul_i32 s84, s84, 0x60000
	s_lshl_b32 s83, s83, 18
	s_waitcnt lgkmcnt(0)
	s_add_u32 s66, s66, s84
	s_addc_u32 s67, s67, 0
	s_add_u32 s68, s68, s83
	s_addc_u32 s69, s69, 0
	s_add_u32 s83, s79, 0
	s_and_b32 s83, s83, 15
	s_lshl_b32 s83, s83, 7
	s_add_u32 s70, s66, s83
	s_addc_u32 s71, s67, 0
	s_add_u32 s72, s68, s83
	s_addc_u32 s73, s69, 0
	s_add_u32 s81, s80, 0x0
	s_add_u32 s82, s80, 0xc000
	s_add_u32 m0, s81, 0x0
	s_nop 0
	global_load_lds_dwordx4 v207, s[70:71]
	s_add_u32 m0, s81, 0x1000
	s_nop 0
	global_load_lds_dwordx4 v206, s[70:71]
	s_add_u32 m0, s81, 0x2000
	s_nop 0
	global_load_lds_dwordx4 v205, s[70:71]
	s_add_u32 m0, s81, 0x3000
	s_nop 0
	global_load_lds_dwordx4 v204, s[70:71]
	s_add_u32 m0, s81, 0x4000
	s_nop 0
	global_load_lds_dwordx4 v203, s[70:71]
	s_add_u32 m0, s81, 0x5000
	s_nop 0
	global_load_lds_dwordx4 v202, s[70:71]
	s_add_u32 m0, s82, 0x0
	s_nop 0
	global_load_lds_dwordx4 v207, s[72:73]
	s_add_u32 m0, s82, 0x1000
	s_nop 0
	global_load_lds_dwordx4 v206, s[72:73]
	s_add_u32 m0, s82, 0x2000
	s_nop 0
	global_load_lds_dwordx4 v205, s[72:73]
	s_add_u32 m0, s82, 0x3000
	s_nop 0
	global_load_lds_dwordx4 v204, s[72:73]
	s_add_u32 s83, s79, 1
	s_and_b32 s83, s83, 15
	s_lshl_b32 s83, s83, 7
	s_add_u32 s70, s66, s83
	s_addc_u32 s71, s67, 0
	s_add_u32 s72, s68, s83
	s_addc_u32 s73, s69, 0
	s_add_u32 s81, s80, 0x6000
	s_add_u32 s82, s80, 0x10000
	s_add_u32 m0, s81, 0x0
	s_nop 0
	global_load_lds_dwordx4 v207, s[70:71]
	s_add_u32 m0, s81, 0x1000
	s_nop 0
	global_load_lds_dwordx4 v206, s[70:71]
	s_add_u32 m0, s81, 0x2000
	s_nop 0
	global_load_lds_dwordx4 v205, s[70:71]
	s_add_u32 m0, s81, 0x3000
	s_nop 0
	global_load_lds_dwordx4 v204, s[70:71]
	s_add_u32 m0, s81, 0x4000
	s_nop 0
	global_load_lds_dwordx4 v203, s[70:71]
	v_mov_b32_e32 v2, 0
	v_mov_b32_e32 v3, 0
	v_mov_b32_e32 v4, 0
	v_mov_b32_e32 v5, 0
	v_mov_b32_e32 v6, 0
	v_mov_b32_e32 v7, 0
	v_mov_b32_e32 v8, 0
	v_mov_b32_e32 v9, 0
	v_mov_b32_e32 v10, 0
	v_mov_b32_e32 v11, 0
	v_mov_b32_e32 v12, 0
	v_mov_b32_e32 v13, 0
	v_mov_b32_e32 v14, 0
	v_mov_b32_e32 v15, 0
	v_mov_b32_e32 v16, 0
	v_mov_b32_e32 v17, 0
	v_mov_b32_e32 v18, 0
	v_mov_b32_e32 v19, 0
	v_mov_b32_e32 v20, 0
	v_mov_b32_e32 v21, 0
	v_mov_b32_e32 v22, 0
	v_mov_b32_e32 v23, 0
	v_mov_b32_e32 v24, 0
	v_mov_b32_e32 v25, 0
	v_mov_b32_e32 v26, 0
	v_mov_b32_e32 v27, 0
	v_mov_b32_e32 v28, 0
	v_mov_b32_e32 v29, 0
	v_mov_b32_e32 v30, 0
	v_mov_b32_e32 v31, 0
	v_mov_b32_e32 v32, 0
	v_mov_b32_e32 v33, 0
	v_mov_b32_e32 v34, 0
	v_mov_b32_e32 v35, 0
	v_mov_b32_e32 v36, 0
	v_mov_b32_e32 v37, 0
	v_mov_b32_e32 v38, 0
	v_mov_b32_e32 v39, 0
	v_mov_b32_e32 v40, 0
	v_mov_b32_e32 v41, 0
	v_mov_b32_e32 v42, 0
	v_mov_b32_e32 v43, 0
	v_mov_b32_e32 v44, 0
	v_mov_b32_e32 v45, 0
	v_mov_b32_e32 v46, 0
	v_mov_b32_e32 v47, 0
	v_mov_b32_e32 v48, 0
	v_mov_b32_e32 v49, 0
	v_mov_b32_e32 v50, 0
	v_mov_b32_e32 v51, 0
	v_mov_b32_e32 v52, 0
	v_mov_b32_e32 v53, 0
	v_mov_b32_e32 v54, 0
	v_mov_b32_e32 v55, 0
	v_mov_b32_e32 v56, 0
	v_mov_b32_e32 v57, 0
	v_mov_b32_e32 v58, 0
	v_mov_b32_e32 v59, 0
	v_mov_b32_e32 v60, 0
	v_mov_b32_e32 v61, 0
	v_mov_b32_e32 v62, 0
	v_mov_b32_e32 v63, 0
	v_mov_b32_e32 v64, 0
	v_mov_b32_e32 v65, 0
	v_mov_b32_e32 v66, 0
	v_mov_b32_e32 v67, 0
	v_mov_b32_e32 v68, 0
	v_mov_b32_e32 v69, 0
	v_mov_b32_e32 v70, 0
	v_mov_b32_e32 v71, 0
	v_mov_b32_e32 v72, 0
	v_mov_b32_e32 v73, 0
	v_mov_b32_e32 v74, 0
	v_mov_b32_e32 v75, 0
	v_mov_b32_e32 v76, 0
	v_mov_b32_e32 v77, 0
	v_mov_b32_e32 v78, 0
	v_mov_b32_e32 v79, 0
	v_mov_b32_e32 v80, 0
	v_mov_b32_e32 v81, 0
	v_mov_b32_e32 v82, 0
	v_mov_b32_e32 v83, 0
	v_mov_b32_e32 v84, 0
	v_mov_b32_e32 v85, 0
	v_mov_b32_e32 v86, 0
	v_mov_b32_e32 v87, 0
	v_mov_b32_e32 v88, 0
	v_mov_b32_e32 v89, 0
	v_mov_b32_e32 v90, 0
	v_mov_b32_e32 v91, 0
	v_mov_b32_e32 v92, 0
	v_mov_b32_e32 v93, 0
	v_mov_b32_e32 v94, 0
	v_mov_b32_e32 v95, 0
	v_mov_b32_e32 v96, 0
	v_mov_b32_e32 v97, 0
	s_waitcnt vmcnt(5)
	s_barrier
	ds_read_b128 v[240:243], v211 offset:0
	ds_read_b128 v[252:255], v215 offset:0
	ds_read_b128 v[236:239], v211 offset:4096
	ds_read_b128 v[248:251], v215 offset:4096
	ds_read_b128 v[244:247], v215 offset:8192
	s_mov_b32 s78, 0

.Lgm_ph17_noprio:
	s_barrier
	s_load_dwordx2 s[66:67], s[0:1], 0x90
	s_load_dwordx2 s[68:69], s[0:1], 0xc0
	v_and_b32_e32 v201, 0x3ff, v0
	v_readfirstlane_b32 s80, v0
	v_and_b32_e32 v200, 31, v201
	v_bfe_u32 v214, v201, 1, 3
	v_bfe_u32 v213, v201, 5, 1
	v_xor_b32_e32 v214, v214, v213
	v_lshlrev_b32_e32 v214, 4, v214
	s_and_b32 s80, s80, 0x3ff
	s_lshr_b32 s83, s80, 6
	s_lshl_b32 s80, s80, 4
	s_lshr_b32 s84, s83, 1
	s_and_b32 s83, s83, 1
	s_mul_i32 s84, s84, 0x3000
	s_lshl_b32 s83, s83, 13
	s_add_u32 s83, s83, 0xc000
	v_lshlrev_b32_e32 v200, 7, v200
	v_or_b32_e32 v200, v200, v214
	v_add_u32_e32 v215, s84, v200
	v_add_u32_e32 v211, s83, v200
	v_xor_b32_e32 v214, 0x20, v215
	v_xor_b32_e32 v210, 0x20, v211
	v_xor_b32_e32 v213, 0x40, v215
	v_xor_b32_e32 v209, 0x40, v211
	v_xor_b32_e32 v212, 0x60, v215
	v_xor_b32_e32 v208, 0x60, v211
	v_bfe_u32 v200, v201, 4, 3
	v_and_b32_e32 v206, 7, v201
	v_xor_b32_e32 v200, v200, v206
	v_lshlrev_b32_e32 v200, 4, v200
	v_lshrrev_b32_e32 v206, 3, v201
	v_lshl_or_b32 v207, v206, 11, v200
	v_add_u32_e32 v206, 0x10000, v207
	v_add_u32_e32 v205, 0x20000, v207
	v_add_u32_e32 v204, 0x30000, v207
	v_add_u32_e32 v203, 0x40000, v207
	v_add_u32_e32 v202, 0x50000, v207
	s_lshr_b32 s83, s35, 6
	s_and_b32 s84, s35, 63
	s_mov_b32 s79, 0
	s_mul_i32 s84, s84, 0x60000
	s_lshl_b32 s83, s83, 18
	s_add_u32 s83, s83, 0x400000
	s_waitcnt lgkmcnt(0)
	s_add_u32 s66, s66, s84
	s_addc_u32 s67, s67, 0
	s_add_u32 s68, s68, s83
	s_addc_u32 s69, s69, 0
	s_add_u32 s83, s79, 0
	s_and_b32 s83, s83, 15
	s_lshl_b32 s83, s83, 7
	s_add_u32 s70, s66, s83
	s_addc_u32 s71, s67, 0
	s_add_u32 s72, s68, s83
	s_addc_u32 s73, s69, 0
	s_add_u32 s81, s80, 0x0
	s_add_u32 s82, s80, 0xc000
	s_add_u32 m0, s81, 0x0
	s_nop 0
	global_load_lds_dwordx4 v207, s[70:71]
	s_add_u32 m0, s81, 0x1000
	s_nop 0
	global_load_lds_dwordx4 v206, s[70:71]
	s_add_u32 m0, s81, 0x2000
	s_nop 0
	global_load_lds_dwordx4 v205, s[70:71]
	s_add_u32 m0, s81, 0x3000
	s_nop 0
	global_load_lds_dwordx4 v204, s[70:71]
	s_add_u32 m0, s81, 0x4000
	s_nop 0
	global_load_lds_dwordx4 v203, s[70:71]
	s_add_u32 m0, s81, 0x5000
	s_nop 0
	global_load_lds_dwordx4 v202, s[70:71]
	s_add_u32 m0, s82, 0x0
	s_nop 0
	global_load_lds_dwordx4 v207, s[72:73]
	s_add_u32 m0, s82, 0x1000
	s_nop 0
	global_load_lds_dwordx4 v206, s[72:73]
	s_add_u32 m0, s82, 0x2000
	s_nop 0
	global_load_lds_dwordx4 v205, s[72:73]
	s_add_u32 m0, s82, 0x3000
	s_nop 0
	global_load_lds_dwordx4 v204, s[72:73]
	s_add_u32 s83, s79, 1
	s_and_b32 s83, s83, 15
	s_lshl_b32 s83, s83, 7
	s_add_u32 s70, s66, s83
	s_addc_u32 s71, s67, 0
	s_add_u32 s72, s68, s83
	s_addc_u32 s73, s69, 0
	s_add_u32 s81, s80, 0x6000
	s_add_u32 s82, s80, 0x10000
	s_add_u32 m0, s81, 0x0
	s_nop 0
	global_load_lds_dwordx4 v207, s[70:71]
	s_add_u32 m0, s81, 0x1000
	s_nop 0
	global_load_lds_dwordx4 v206, s[70:71]
	s_add_u32 m0, s81, 0x2000
	s_nop 0
	global_load_lds_dwordx4 v205, s[70:71]
	s_add_u32 m0, s81, 0x3000
	s_nop 0
	global_load_lds_dwordx4 v204, s[70:71]
	s_add_u32 m0, s81, 0x4000
	s_nop 0
	global_load_lds_dwordx4 v203, s[70:71]
	v_mov_b32_e32 v2, 0
	v_mov_b32_e32 v3, 0
	v_mov_b32_e32 v4, 0
	v_mov_b32_e32 v5, 0
	v_mov_b32_e32 v6, 0
	v_mov_b32_e32 v7, 0
	v_mov_b32_e32 v8, 0
	v_mov_b32_e32 v9, 0
	v_mov_b32_e32 v10, 0
	v_mov_b32_e32 v11, 0
	v_mov_b32_e32 v12, 0
	v_mov_b32_e32 v13, 0
	v_mov_b32_e32 v14, 0
	v_mov_b32_e32 v15, 0
	v_mov_b32_e32 v16, 0
	v_mov_b32_e32 v17, 0
	v_mov_b32_e32 v18, 0
	v_mov_b32_e32 v19, 0
	v_mov_b32_e32 v20, 0
	v_mov_b32_e32 v21, 0
	v_mov_b32_e32 v22, 0
	v_mov_b32_e32 v23, 0
	v_mov_b32_e32 v24, 0
	v_mov_b32_e32 v25, 0
	v_mov_b32_e32 v26, 0
	v_mov_b32_e32 v27, 0
	v_mov_b32_e32 v28, 0
	v_mov_b32_e32 v29, 0
	v_mov_b32_e32 v30, 0
	v_mov_b32_e32 v31, 0
	v_mov_b32_e32 v32, 0
	v_mov_b32_e32 v33, 0
	v_mov_b32_e32 v34, 0
	v_mov_b32_e32 v35, 0
	v_mov_b32_e32 v36, 0
	v_mov_b32_e32 v37, 0
	v_mov_b32_e32 v38, 0
	v_mov_b32_e32 v39, 0
	v_mov_b32_e32 v40, 0
	v_mov_b32_e32 v41, 0
	v_mov_b32_e32 v42, 0
	v_mov_b32_e32 v43, 0
	v_mov_b32_e32 v44, 0
	v_mov_b32_e32 v45, 0
	v_mov_b32_e32 v46, 0
	v_mov_b32_e32 v47, 0
	v_mov_b32_e32 v48, 0
	v_mov_b32_e32 v49, 0
	v_mov_b32_e32 v50, 0
	v_mov_b32_e32 v51, 0
	v_mov_b32_e32 v52, 0
	v_mov_b32_e32 v53, 0
	v_mov_b32_e32 v54, 0
	v_mov_b32_e32 v55, 0
	v_mov_b32_e32 v56, 0
	v_mov_b32_e32 v57, 0
	v_mov_b32_e32 v58, 0
	v_mov_b32_e32 v59, 0
	v_mov_b32_e32 v60, 0
	v_mov_b32_e32 v61, 0
	v_mov_b32_e32 v62, 0
	v_mov_b32_e32 v63, 0
	v_mov_b32_e32 v64, 0
	v_mov_b32_e32 v65, 0
	v_mov_b32_e32 v66, 0
	v_mov_b32_e32 v67, 0
	v_mov_b32_e32 v68, 0
	v_mov_b32_e32 v69, 0
	v_mov_b32_e32 v70, 0
	v_mov_b32_e32 v71, 0
	v_mov_b32_e32 v72, 0
	v_mov_b32_e32 v73, 0
	v_mov_b32_e32 v74, 0
	v_mov_b32_e32 v75, 0
	v_mov_b32_e32 v76, 0
	v_mov_b32_e32 v77, 0
	v_mov_b32_e32 v78, 0
	v_mov_b32_e32 v79, 0
	v_mov_b32_e32 v80, 0
	v_mov_b32_e32 v81, 0
	v_mov_b32_e32 v82, 0
	v_mov_b32_e32 v83, 0
	v_mov_b32_e32 v84, 0
	v_mov_b32_e32 v85, 0
	v_mov_b32_e32 v86, 0
	v_mov_b32_e32 v87, 0
	v_mov_b32_e32 v88, 0
	v_mov_b32_e32 v89, 0
	v_mov_b32_e32 v90, 0
	v_mov_b32_e32 v91, 0
	v_mov_b32_e32 v92, 0
	v_mov_b32_e32 v93, 0
	v_mov_b32_e32 v94, 0
	v_mov_b32_e32 v95, 0
	v_mov_b32_e32 v96, 0
	v_mov_b32_e32 v97, 0
	s_waitcnt vmcnt(5)
	s_barrier
	ds_read_b128 v[240:243], v211 offset:0
	ds_read_b128 v[252:255], v215 offset:0
	ds_read_b128 v[236:239], v211 offset:4096
	ds_read_b128 v[248:251], v215 offset:4096
	ds_read_b128 v[244:247], v215 offset:8192
	s_mov_b32 s78, 0

.Lgm_ph20_noprio:
	s_barrier
	s_load_dwordx2 s[66:67], s[0:1], 0x118
	s_load_dwordx2 s[68:69], s[0:1], 0xd0
	v_and_b32_e32 v201, 0x3ff, v0
	v_readfirstlane_b32 s80, v0
	v_and_b32_e32 v200, 31, v201
	v_bfe_u32 v214, v201, 1, 3
	v_bfe_u32 v213, v201, 5, 1
	v_xor_b32_e32 v214, v214, v213
	v_lshlrev_b32_e32 v214, 4, v214
	s_and_b32 s80, s80, 0x3ff
	s_lshr_b32 s83, s80, 6
	s_lshl_b32 s80, s80, 4
	s_lshr_b32 s84, s83, 1
	s_and_b32 s83, s83, 1
	s_mul_i32 s84, s84, 0x3000
	s_lshl_b32 s83, s83, 13
	s_add_u32 s83, s83, 0xc000
	v_lshlrev_b32_e32 v200, 7, v200
	v_or_b32_e32 v200, v200, v214
	v_add_u32_e32 v215, s84, v200
	v_add_u32_e32 v211, s83, v200
	v_xor_b32_e32 v214, 0x20, v215
	v_xor_b32_e32 v210, 0x20, v211
	v_xor_b32_e32 v213, 0x40, v215
	v_xor_b32_e32 v209, 0x40, v211
	v_xor_b32_e32 v212, 0x60, v215
	v_xor_b32_e32 v208, 0x60, v211
	v_bfe_u32 v200, v201, 4, 3
	v_and_b32_e32 v206, 7, v201
	v_xor_b32_e32 v200, v200, v206
	v_lshlrev_b32_e32 v200, 4, v200
	v_lshrrev_b32_e32 v206, 3, v201
	v_lshl_or_b32 v207, v206, 11, v200
	v_add_u32_e32 v206, 0x10000, v207
	v_add_u32_e32 v205, 0x20000, v207
	v_add_u32_e32 v204, 0x30000, v207
	v_add_u32_e32 v203, 0x40000, v207
	v_add_u32_e32 v202, 0x50000, v207
	s_lshr_b32 s83, s2, 6
	s_and_b32 s84, s2, 63
	s_mov_b32 s79, 0
	s_mul_i32 s84, s84, 0x60000
	s_lshl_b32 s83, s83, 18
	s_add_u32 s83, s83, 0x200000
	s_waitcnt lgkmcnt(0)
	s_add_u32 s66, s66, s84
	s_addc_u32 s67, s67, 0
	s_add_u32 s68, s68, s83
	s_addc_u32 s69, s69, 0
	s_add_u32 s83, s79, 0
	s_and_b32 s83, s83, 15
	s_lshl_b32 s83, s83, 7
	s_add_u32 s70, s66, s83
	s_addc_u32 s71, s67, 0
	s_add_u32 s72, s68, s83
	s_addc_u32 s73, s69, 0
	s_add_u32 s81, s80, 0x0
	s_add_u32 s82, s80, 0xc000
	s_add_u32 m0, s81, 0x0
	s_nop 0
	global_load_lds_dwordx4 v207, s[70:71]
	s_add_u32 m0, s81, 0x1000
	s_nop 0
	global_load_lds_dwordx4 v206, s[70:71]
	s_add_u32 m0, s81, 0x2000
	s_nop 0
	global_load_lds_dwordx4 v205, s[70:71]
	s_add_u32 m0, s81, 0x3000
	s_nop 0
	global_load_lds_dwordx4 v204, s[70:71]
	s_add_u32 m0, s81, 0x4000
	s_nop 0
	global_load_lds_dwordx4 v203, s[70:71]
	s_add_u32 m0, s81, 0x5000
	s_nop 0
	global_load_lds_dwordx4 v202, s[70:71]
	s_add_u32 m0, s82, 0x0
	s_nop 0
	global_load_lds_dwordx4 v207, s[72:73]
	s_add_u32 m0, s82, 0x1000
	s_nop 0
	global_load_lds_dwordx4 v206, s[72:73]
	s_add_u32 m0, s82, 0x2000
	s_nop 0
	global_load_lds_dwordx4 v205, s[72:73]
	s_add_u32 m0, s82, 0x3000
	s_nop 0
	global_load_lds_dwordx4 v204, s[72:73]
	s_add_u32 s83, s79, 1
	s_and_b32 s83, s83, 15
	s_lshl_b32 s83, s83, 7
	s_add_u32 s70, s66, s83
	s_addc_u32 s71, s67, 0
	s_add_u32 s72, s68, s83
	s_addc_u32 s73, s69, 0
	s_add_u32 s81, s80, 0x6000
	s_add_u32 s82, s80, 0x10000
	s_add_u32 m0, s81, 0x0
	s_nop 0
	global_load_lds_dwordx4 v207, s[70:71]
	s_add_u32 m0, s81, 0x1000
	s_nop 0
	global_load_lds_dwordx4 v206, s[70:71]
	s_add_u32 m0, s81, 0x2000
	s_nop 0
	global_load_lds_dwordx4 v205, s[70:71]
	s_add_u32 m0, s81, 0x3000
	s_nop 0
	global_load_lds_dwordx4 v204, s[70:71]
	s_add_u32 m0, s81, 0x4000
	s_nop 0
	global_load_lds_dwordx4 v203, s[70:71]
	v_mov_b32_e32 v2, 0
	v_mov_b32_e32 v3, 0
	v_mov_b32_e32 v4, 0
	v_mov_b32_e32 v5, 0
	v_mov_b32_e32 v6, 0
	v_mov_b32_e32 v7, 0
	v_mov_b32_e32 v8, 0
	v_mov_b32_e32 v9, 0
	v_mov_b32_e32 v10, 0
	v_mov_b32_e32 v11, 0
	v_mov_b32_e32 v12, 0
	v_mov_b32_e32 v13, 0
	v_mov_b32_e32 v14, 0
	v_mov_b32_e32 v15, 0
	v_mov_b32_e32 v16, 0
	v_mov_b32_e32 v17, 0
	v_mov_b32_e32 v18, 0
	v_mov_b32_e32 v19, 0
	v_mov_b32_e32 v20, 0
	v_mov_b32_e32 v21, 0
	v_mov_b32_e32 v22, 0
	v_mov_b32_e32 v23, 0
	v_mov_b32_e32 v24, 0
	v_mov_b32_e32 v25, 0
	v_mov_b32_e32 v26, 0
	v_mov_b32_e32 v27, 0
	v_mov_b32_e32 v28, 0
	v_mov_b32_e32 v29, 0
	v_mov_b32_e32 v30, 0
	v_mov_b32_e32 v31, 0
	v_mov_b32_e32 v32, 0
	v_mov_b32_e32 v33, 0
	v_mov_b32_e32 v34, 0
	v_mov_b32_e32 v35, 0
	v_mov_b32_e32 v36, 0
	v_mov_b32_e32 v37, 0
	v_mov_b32_e32 v38, 0
	v_mov_b32_e32 v39, 0
	v_mov_b32_e32 v40, 0
	v_mov_b32_e32 v41, 0
	v_mov_b32_e32 v42, 0
	v_mov_b32_e32 v43, 0
	v_mov_b32_e32 v44, 0
	v_mov_b32_e32 v45, 0
	v_mov_b32_e32 v46, 0
	v_mov_b32_e32 v47, 0
	v_mov_b32_e32 v48, 0
	v_mov_b32_e32 v49, 0
	v_mov_b32_e32 v50, 0
	v_mov_b32_e32 v51, 0
	v_mov_b32_e32 v52, 0
	v_mov_b32_e32 v53, 0
	v_mov_b32_e32 v54, 0
	v_mov_b32_e32 v55, 0
	v_mov_b32_e32 v56, 0
	v_mov_b32_e32 v57, 0
	v_mov_b32_e32 v58, 0
	v_mov_b32_e32 v59, 0
	v_mov_b32_e32 v60, 0
	v_mov_b32_e32 v61, 0
	v_mov_b32_e32 v62, 0
	v_mov_b32_e32 v63, 0
	v_mov_b32_e32 v64, 0
	v_mov_b32_e32 v65, 0
	v_mov_b32_e32 v66, 0
	v_mov_b32_e32 v67, 0
	v_mov_b32_e32 v68, 0
	v_mov_b32_e32 v69, 0
	v_mov_b32_e32 v70, 0
	v_mov_b32_e32 v71, 0
	v_mov_b32_e32 v72, 0
	v_mov_b32_e32 v73, 0
	v_mov_b32_e32 v74, 0
	v_mov_b32_e32 v75, 0
	v_mov_b32_e32 v76, 0
	v_mov_b32_e32 v77, 0
	v_mov_b32_e32 v78, 0
	v_mov_b32_e32 v79, 0
	v_mov_b32_e32 v80, 0
	v_mov_b32_e32 v81, 0
	v_mov_b32_e32 v82, 0
	v_mov_b32_e32 v83, 0
	v_mov_b32_e32 v84, 0
	v_mov_b32_e32 v85, 0
	v_mov_b32_e32 v86, 0
	v_mov_b32_e32 v87, 0
	v_mov_b32_e32 v88, 0
	v_mov_b32_e32 v89, 0
	v_mov_b32_e32 v90, 0
	v_mov_b32_e32 v91, 0
	v_mov_b32_e32 v92, 0
	v_mov_b32_e32 v93, 0
	v_mov_b32_e32 v94, 0
	v_mov_b32_e32 v95, 0
	v_mov_b32_e32 v96, 0
	v_mov_b32_e32 v97, 0
	s_waitcnt vmcnt(5)
	s_barrier
	ds_read_b128 v[240:243], v211 offset:0
	ds_read_b128 v[252:255], v215 offset:0
	ds_read_b128 v[236:239], v211 offset:4096
	ds_read_b128 v[248:251], v215 offset:4096
	ds_read_b128 v[244:247], v215 offset:8192
	s_mov_b32 s78, 0
